# grid barrier: per-CU L1 invalidate issued at arrival (overlaps the wait; no cached loads are issued between arrival and release) instead of after release
# speedup vs baseline: 1.0511x; 1.0095x over previous
.LBB0_237:
	s_or_b64 exec, exec, s[6:7]
	s_waitcnt vmcnt(0)
	s_nop 0
	global_atomic_add v[172:173], v212, off
	s_waitcnt vmcnt(0)

.LBB0_335:
	global_atomic_add v4, v[170:171], v212, off sc0
	v_cvt_f32_u32_e32 v2, v3
	v_sub_u32_e32 v5, 0, v3
	v_rcp_iflag_f32_e32 v2, v2
	s_nop 0
	v_mul_f32_e32 v2, 0x4f7ffffe, v2
	v_cvt_u32_f32_e32 v2, v2
	v_mul_lo_u32 v5, v5, v2
	v_mul_hi_u32 v5, v2, v5
	v_add_u32_e32 v2, v2, v5
	s_waitcnt vmcnt(0)
	buffer_inv sc1
	v_mul_hi_u32 v2, v4, v2
	v_mul_lo_u32 v5, v2, v3
	v_sub_u32_e32 v5, v4, v5
	v_add_u32_e32 v6, 1, v2
	v_sub_u32_e32 v7, v5, v3
	v_cmp_ge_u32_e32 vcc, v5, v3
	v_add_u32_e32 v4, 1, v4
	s_nop 0
	v_cndmask_b32_e32 v2, v2, v6, vcc
	v_cndmask_b32_e32 v5, v5, v7, vcc
	v_add_u32_e32 v6, 1, v2
	v_cmp_ge_u32_e32 vcc, v5, v3
	s_nop 1
	v_cndmask_b32_e32 v2, v2, v6, vcc
	v_mul_lo_u32 v5, v3, v2
	v_add_u32_e32 v3, v5, v3
	v_cmp_ne_u32_e32 vcc, v4, v3
	s_and_saveexec_b64 s[4:5], vcc
	s_xor_b64 s[6:7], exec, s[4:5]
	s_cbranch_execz .LBB0_349
	s_waitcnt lgkmcnt(0)
	v_mad_u32_u24 v6, v2, v1, v1
	v_mov_b32_e32 v1, 0x3200
	global_load_dword v1, v1, s[22:23] sc1
	s_waitcnt vmcnt(0)
	v_cmp_gt_u32_e32 vcc, v6, v1
	s_and_saveexec_b64 s[8:9], vcc
	s_cbranch_execz .LBB0_348
	s_mov_b32 s3, 1
	s_mov_b64 s[24:25], 0
	s_branch .LBB0_339

.LBB0_348:
	s_or_b64 exec, exec, s[8:9]
	s_waitcnt vmcnt(0)
	s_nop 0
	s_waitcnt vmcnt(0)

.LBB0_366:
	s_or_b64 exec, exec, s[8:9]
	s_waitcnt vmcnt(0)
	s_nop 0
	global_atomic_add v[172:173], v212, off
	s_waitcnt vmcnt(0)

.LBB0_472:
	global_atomic_add v4, v[170:171], v212, off sc0
	v_cvt_f32_u32_e32 v1, v3
	v_sub_u32_e32 v5, 0, v3
	v_rcp_iflag_f32_e32 v1, v1
	s_nop 0
	v_mul_f32_e32 v1, 0x4f7ffffe, v1
	v_cvt_u32_f32_e32 v1, v1
	v_mul_lo_u32 v5, v5, v1
	v_mul_hi_u32 v5, v1, v5
	v_add_u32_e32 v1, v1, v5
	s_waitcnt vmcnt(0)
	buffer_inv sc1
	v_mul_hi_u32 v1, v4, v1
	v_mul_lo_u32 v5, v1, v3
	v_sub_u32_e32 v5, v4, v5
	v_add_u32_e32 v6, 1, v1
	v_cmp_ge_u32_e32 vcc, v5, v3
	v_add_u32_e32 v4, 1, v4
	s_nop 0
	v_cndmask_b32_e32 v1, v1, v6, vcc
	v_sub_u32_e32 v6, v5, v3
	v_cndmask_b32_e32 v5, v5, v6, vcc
	v_add_u32_e32 v6, 1, v1
	v_cmp_ge_u32_e32 vcc, v5, v3
	s_nop 1
	v_cndmask_b32_e32 v1, v1, v6, vcc
	v_mul_lo_u32 v5, v3, v1
	v_add_u32_e32 v3, v5, v3
	v_cmp_ne_u32_e32 vcc, v4, v3
	s_and_saveexec_b64 s[4:5], vcc
	s_xor_b64 s[6:7], exec, s[4:5]
	s_cbranch_execz .LBB0_486
	s_waitcnt lgkmcnt(0)
	v_mad_u32_u24 v6, v1, v2, v2
	v_mov_b32_e32 v2, 0x3200
	global_load_dword v2, v2, s[22:23] sc1
	s_waitcnt vmcnt(0)
	v_cmp_gt_u32_e32 vcc, v6, v2
	s_and_saveexec_b64 s[8:9], vcc
	s_cbranch_execz .LBB0_485
	s_mov_b32 s3, 1
	s_mov_b64 s[36:37], 0
	s_branch .LBB0_476

.LBB0_736:
	global_atomic_add v4, v[170:171], v212, off sc0
	v_cvt_f32_u32_e32 v1, v3
	v_sub_u32_e32 v5, 0, v3
	v_rcp_iflag_f32_e32 v1, v1
	s_nop 0
	v_mul_f32_e32 v1, 0x4f7ffffe, v1
	v_cvt_u32_f32_e32 v1, v1
	v_mul_lo_u32 v5, v5, v1
	v_mul_hi_u32 v5, v1, v5
	v_add_u32_e32 v1, v1, v5
	s_waitcnt vmcnt(0)
	buffer_inv sc1
	v_mul_hi_u32 v1, v4, v1
	v_mul_lo_u32 v5, v1, v3
	v_sub_u32_e32 v5, v4, v5
	v_add_u32_e32 v6, 1, v1
	v_cmp_ge_u32_e32 vcc, v5, v3
	v_add_u32_e32 v4, 1, v4
	s_nop 0
	v_cndmask_b32_e32 v1, v1, v6, vcc
	v_sub_u32_e32 v6, v5, v3
	v_cndmask_b32_e32 v5, v5, v6, vcc
	v_add_u32_e32 v6, 1, v1
	v_cmp_ge_u32_e32 vcc, v5, v3
	s_nop 1
	v_cndmask_b32_e32 v1, v1, v6, vcc
	v_mul_lo_u32 v5, v3, v1
	v_add_u32_e32 v3, v5, v3
	v_cmp_ne_u32_e32 vcc, v4, v3
	s_and_saveexec_b64 s[4:5], vcc
	s_xor_b64 s[6:7], exec, s[4:5]
	s_cbranch_execz .LBB0_750
	s_waitcnt lgkmcnt(0)
	v_mad_u32_u24 v6, v1, v2, v2
	v_mov_b32_e32 v2, 0x3200
	global_load_dword v2, v2, s[22:23] sc1
	s_waitcnt vmcnt(0)
	v_cmp_gt_u32_e32 vcc, v6, v2
	s_and_saveexec_b64 s[8:9], vcc
	s_cbranch_execz .LBB0_749
	s_mov_b32 s3, 1
	s_mov_b64 s[24:25], 0
	s_branch .LBB0_740
